# attention selected-branch PV: V fragments via ds_read_b64 pairs (full LDS rate) with 3 extra fragment buffers prefetched; bias1 loop deeper
# speedup vs baseline: 1.0017x; 1.0017x over previous
; template <int MODE> ...
;     ...
;         ATT_SOFTMAX(X0, 0);
;         if (MODE >= 2) ATT_PV(X0, 0);
;         ATT_SOFTMAX(X1, 1);
;         if (MODE >= 2) ATT_PV(X1, 1);
.LBB0_587:
	v_add_u32_e32 v96, s19, v232
	v_add_u32_e32 v99, v96, v233
	v_add_u32_e32 v96, 0x4000, v99
	v_add_u32_e32 v97, 0x5000, v99
	v_add_u32_e32 v98, 0x6000, v99
	v_add_u32_e32 v99, 0x7000, v99
	ds_read_b64 v[240:241], v96 offset:1024
	ds_read_b64 v[242:243], v96 offset:1040
	ds_read_b64 v[244:245], v97 offset:1280
	ds_read_b64 v[246:247], v97 offset:1296
	ds_read_b64 v[248:249], v98 offset:1536
	ds_read_b64 v[250:251], v98 offset:1552
	v_cvt_pk_bf16_f32 v80, v80, v81
	v_cvt_pk_bf16_f32 v81, v82, v83
	v_cvt_pk_bf16_f32 v82, v84, v85
	v_cvt_pk_bf16_f32 v83, v86, v87
	ds_read_b64 v[84:85], v99 offset:1792
	ds_read_b64 v[86:87], v99 offset:1808
	ds_read_b64 v[100:101], v96 offset:1056
	ds_read_b64 v[102:103], v96 offset:1072
	v_exp_f32_e32 v64, v64
	v_exp_f32_e32 v65, v65
	v_exp_f32_e32 v66, v66
	v_exp_f32_e32 v67, v67
	s_waitcnt lgkmcnt(8)
	v_mfma_f32_32x32x16_bf16 v[48:63], v[240:243], v[80:83], v[48:63]
	ds_read_b64 v[240:241], v97 offset:1312
	ds_read_b64 v[242:243], v97 offset:1328
	v_exp_f32_e32 v68, v68
	v_exp_f32_e32 v69, v69
	v_exp_f32_e32 v70, v70
	s_waitcnt lgkmcnt(8)
	v_mfma_f32_32x32x16_bf16 v[32:47], v[244:247], v[80:83], v[32:47]
	ds_read_b64 v[244:245], v98 offset:1568
	ds_read_b64 v[246:247], v98 offset:1584
	v_exp_f32_e32 v71, v71
	v_exp_f32_e32 v72, v72
	v_exp_f32_e32 v73, v73
	s_waitcnt lgkmcnt(8)
	v_mfma_f32_32x32x16_bf16 v[16:31], v[248:251], v[80:83], v[16:31]
	ds_read_b64 v[248:249], v99 offset:1824
	ds_read_b64 v[250:251], v99 offset:1840
	v_exp_f32_e32 v74, v74
	v_exp_f32_e32 v75, v75
	v_exp_f32_e32 v76, v76
	s_waitcnt lgkmcnt(8)
	v_mfma_f32_32x32x16_bf16 v[0:15], v[84:87], v[80:83], v[0:15]
	v_exp_f32_e32 v77, v77
	v_exp_f32_e32 v78, v78
	v_exp_f32_e32 v79, v79
	v_cvt_pk_bf16_f32 v80, v88, v89
	v_cvt_pk_bf16_f32 v81, v90, v91
	v_cvt_pk_bf16_f32 v82, v92, v93
	v_cvt_pk_bf16_f32 v83, v94, v95
	s_mov_b64 s[10:11], -1
	s_andn2_b64 vcc, exec, s[8:9]
	s_waitcnt lgkmcnt(6)
	v_mfma_f32_32x32x16_bf16 v[48:63], v[100:103], v[80:83], v[48:63]
	s_waitcnt lgkmcnt(4)
	v_mfma_f32_32x32x16_bf16 v[32:47], v[240:243], v[80:83], v[32:47]
	ds_read_b64 v[240:241], v96 offset:1088
	ds_read_b64 v[242:243], v96 offset:1104
	s_waitcnt lgkmcnt(4)
	v_mfma_f32_32x32x16_bf16 v[16:31], v[244:247], v[80:83], v[16:31]
	ds_read_b64 v[244:245], v97 offset:1344
	ds_read_b64 v[246:247], v97 offset:1360
	s_waitcnt lgkmcnt(4)
	v_mfma_f32_32x32x16_bf16 v[0:15], v[248:251], v[80:83], v[0:15]
	ds_read_b64 v[248:249], v98 offset:1600
	ds_read_b64 v[250:251], v98 offset:1616
	s_cbranch_vccnz .LBB0_589
	v_cmp_lt_i32_e32 vcc, 31, v235
	s_and_b64 vcc, vcc, s[2:3]
	s_mov_b64 s[10:11], 0
	v_cndmask_b32_e32 v80, 0, v64, vcc
	v_cmp_lt_i32_e32 vcc, 32, v235
	s_and_b64 vcc, vcc, s[2:3]
	v_add_f32_e32 v82, v80, v236
	v_cndmask_b32_e32 v81, 0, v65, vcc
	v_cmp_lt_i32_e32 vcc, 33, v235
	s_and_b64 vcc, vcc, s[2:3]
	v_add_f32_e32 v83, v81, v82
	v_cndmask_b32_e32 v82, 0, v66, vcc
	v_cmp_lt_i32_e32 vcc, 34, v235
	s_and_b64 vcc, vcc, s[2:3]
	v_add_f32_e32 v84, v82, v83
	v_cndmask_b32_e32 v83, 0, v67, vcc
	v_cmp_lt_i32_e32 vcc, 39, v235
	s_and_b64 vcc, vcc, s[2:3]
	v_add_f32_e32 v85, v83, v84
	v_cndmask_b32_e32 v84, 0, v68, vcc
	v_cmp_lt_i32_e32 vcc, 40, v235
	s_and_b64 vcc, vcc, s[2:3]
	v_add_f32_e32 v86, v84, v85
	v_cndmask_b32_e32 v85, 0, v69, vcc
	v_cmp_lt_i32_e32 vcc, 41, v235
	s_and_b64 vcc, vcc, s[2:3]
	v_add_f32_e32 v87, v85, v86
	v_cndmask_b32_e32 v86, 0, v70, vcc
	v_cmp_lt_i32_e32 vcc, 42, v235
	s_and_b64 vcc, vcc, s[2:3]
	v_add_f32_e32 v88, v86, v87
	v_cndmask_b32_e32 v87, 0, v71, vcc
	v_cmp_lt_i32_e32 vcc, 47, v235
	s_and_b64 vcc, vcc, s[2:3]
	v_add_f32_e32 v89, v87, v88
	v_cndmask_b32_e32 v88, 0, v72, vcc
	v_cmp_lt_i32_e32 vcc, 48, v235
	s_and_b64 vcc, vcc, s[2:3]
	v_add_f32_e32 v90, v88, v89
	v_cndmask_b32_e32 v89, 0, v73, vcc
	v_cmp_lt_i32_e32 vcc, 49, v235
	s_and_b64 vcc, vcc, s[2:3]
	v_add_f32_e32 v91, v89, v90
	v_cndmask_b32_e32 v90, 0, v74, vcc
	v_cmp_lt_i32_e32 vcc, 50, v235
	s_and_b64 vcc, vcc, s[2:3]
	v_add_f32_e32 v92, v90, v91
	v_cndmask_b32_e32 v91, 0, v75, vcc
	v_cmp_lt_i32_e32 vcc, 55, v235
	s_and_b64 vcc, vcc, s[2:3]
	v_add_f32_e32 v93, v91, v92
	v_cndmask_b32_e32 v92, 0, v76, vcc
	v_cmp_lt_i32_e32 vcc, 56, v235
	s_and_b64 vcc, vcc, s[2:3]
	v_add_f32_e32 v94, v92, v93
	v_cndmask_b32_e32 v93, 0, v77, vcc
	v_cmp_lt_i32_e32 vcc, 57, v235
	s_and_b64 vcc, vcc, s[2:3]
	v_add_f32_e32 v95, v93, v94
	v_cndmask_b32_e32 v94, 0, v78, vcc
	v_cmp_lt_i32_e32 vcc, 58, v235
	s_and_b64 vcc, vcc, s[2:3]
	v_add_f32_e32 v100, v94, v95
	v_cndmask_b32_e32 v95, 0, v79, vcc
	v_add_f32_e32 v100, v95, v100

; template <int MODE> ...
;     ...
;         ATT_SOFTMAX(X0, 0);
;         if (MODE >= 2) ATT_PV(X0, 0);
;         ATT_SOFTMAX(X1, 1);
;         if (MODE >= 2) ATT_PV(X1, 1);
;         if (MODE != 1) l_run += rs;
.LBB0_591:
	ds_read_b64 v[64:65], v99 offset:1856
	ds_read_b64 v[66:67], v99 offset:1872
	ds_read_b64 v[72:73], v96 offset:1120
	ds_read_b64 v[74:75], v96 offset:1136
	ds_read_b64 v[76:77], v97 offset:1376
	ds_read_b64 v[78:79], v97 offset:1392
	v_cvt_pk_bf16_f32 v68, v80, v81
	v_cvt_pk_bf16_f32 v69, v82, v83
	v_cvt_pk_bf16_f32 v70, v84, v85
	v_cvt_pk_bf16_f32 v71, v86, v87
	v_add_f32_e32 v193, v193, v100
	s_waitcnt lgkmcnt(10)
	v_mfma_f32_32x32x16_bf16 v[48:63], v[240:243], v[68:71], v[48:63]
	s_waitcnt lgkmcnt(8)
	v_mfma_f32_32x32x16_bf16 v[32:47], v[244:247], v[68:71], v[32:47]
	ds_read_b64 v[240:241], v98 offset:1632
	ds_read_b64 v[242:243], v98 offset:1648
	s_waitcnt lgkmcnt(8)
	v_mfma_f32_32x32x16_bf16 v[16:31], v[248:251], v[68:71], v[16:31]
	ds_read_b64 v[244:245], v99 offset:1888
	ds_read_b64 v[246:247], v99 offset:1904
	s_waitcnt lgkmcnt(8)
	v_mfma_f32_32x32x16_bf16 v[0:15], v[64:67], v[68:71], v[0:15]
	v_cvt_pk_bf16_f32 v68, v88, v89
	v_cvt_pk_bf16_f32 v69, v90, v91
	v_cvt_pk_bf16_f32 v70, v92, v93
	v_cvt_pk_bf16_f32 v71, v94, v95
	s_waitcnt lgkmcnt(6)
	s_nop 0
	v_mfma_f32_32x32x16_bf16 v[48:63], v[72:75], v[68:71], v[48:63]
	s_waitcnt lgkmcnt(4)
	v_mfma_f32_32x32x16_bf16 v[32:47], v[76:79], v[68:71], v[32:47]
	s_waitcnt lgkmcnt(2)
	v_mfma_f32_32x32x16_bf16 v[16:31], v[240:243], v[68:71], v[16:31]
	s_waitcnt lgkmcnt(0)
	v_mfma_f32_32x32x16_bf16 v[0:15], v[244:247], v[68:71], v[0:15]
	s_andn2_b64 vcc, exec, s[6:7]
	s_cbranch_vccz .LBB0_594
	s_branch .LBB0_579
